# diff-attention lambda dot products: 32 serialized load round trips replaced by batched loads + ordered fma chain
# speedup vs baseline: 1.0737x; 1.0095x over previous
.LBB0_569:
	s_load_dwordx8 s[12:19], s[4:5], 0x58
	s_mov_b32 s27, s55
	s_lshl_b64 s[0:1], s[26:27], 7
	v_mov_b32_e32 v1, 0
	v_mov_b32_e32 v0, 0
	s_waitcnt lgkmcnt(0)
	s_add_u32 s2, s18, s0
	s_addc_u32 s3, s19, s1
	s_add_u32 s6, s16, s0
	s_addc_u32 s7, s17, s1
	s_add_u32 s8, s14, s0
	s_addc_u32 s9, s15, s1
	s_add_u32 s11, s12, s0
	s_addc_u32 s12, s13, s1
	s_mov_b64 s[0:1], 0
	s_mov_b32 s14, s11
	s_mov_b32 s15, s12
	global_load_dwordx4 v[102:105], v177, s[14:15]
	global_load_dwordx4 v[106:109], v177, s[14:15] offset:16
	global_load_dwordx4 v[110:113], v177, s[14:15] offset:32
	global_load_dwordx4 v[114:117], v177, s[14:15] offset:48
	global_load_dwordx4 v[118:121], v177, s[14:15] offset:64
	global_load_dwordx4 v[122:125], v177, s[14:15] offset:80
	global_load_dwordx4 v[126:129], v177, s[14:15] offset:96
	global_load_dwordx4 v[130:133], v177, s[14:15] offset:112
	global_load_dwordx4 v[134:137], v177, s[8:9]
	global_load_dwordx4 v[138:141], v177, s[8:9] offset:16
	global_load_dwordx4 v[142:145], v177, s[8:9] offset:32
	global_load_dwordx4 v[146:149], v177, s[8:9] offset:48
	global_load_dwordx4 v[150:153], v177, s[8:9] offset:64
	global_load_dwordx4 v[154:157], v177, s[8:9] offset:80
	global_load_dwordx4 v[158:161], v177, s[8:9] offset:96
	global_load_dwordx4 v[162:165], v177, s[8:9] offset:112
	global_load_dwordx4 v[204:207], v177, s[6:7]
	global_load_dwordx4 v[208:211], v177, s[6:7] offset:16
	global_load_dwordx4 v[212:215], v177, s[6:7] offset:32
	global_load_dwordx4 v[216:219], v177, s[6:7] offset:48
	global_load_dwordx4 v[220:223], v177, s[6:7] offset:64
	global_load_dwordx4 v[224:227], v177, s[6:7] offset:80
	global_load_dwordx4 v[228:231], v177, s[6:7] offset:96
	global_load_dwordx4 v[232:235], v177, s[6:7] offset:112
	global_load_dwordx4 v[236:239], v177, s[2:3]
	global_load_dwordx4 v[240:243], v177, s[2:3] offset:16
	global_load_dwordx4 v[56:59], v177, s[2:3] offset:32
	global_load_dwordx4 v[60:63], v177, s[2:3] offset:48
	global_load_dwordx4 v[64:67], v177, s[2:3] offset:64
	global_load_dwordx4 v[68:71], v177, s[2:3] offset:80
	global_load_dwordx4 v[72:75], v177, s[2:3] offset:96
	global_load_dwordx4 v[76:79], v177, s[2:3] offset:112
	s_waitcnt vmcnt(0)
	v_fma_f32 v0, v102, v134, v0
	v_fma_f32 v1, v204, v236, v1
	v_fma_f32 v0, v103, v135, v0
	v_fma_f32 v1, v205, v237, v1
	v_fma_f32 v0, v104, v136, v0
	v_fma_f32 v1, v206, v238, v1
	v_fma_f32 v0, v105, v137, v0
	v_fma_f32 v1, v207, v239, v1
	v_fma_f32 v0, v106, v138, v0
	v_fma_f32 v1, v208, v240, v1
	v_fma_f32 v0, v107, v139, v0
	v_fma_f32 v1, v209, v241, v1
	v_fma_f32 v0, v108, v140, v0
	v_fma_f32 v1, v210, v242, v1
	v_fma_f32 v0, v109, v141, v0
	v_fma_f32 v1, v211, v243, v1
	v_fma_f32 v0, v110, v142, v0
	v_fma_f32 v1, v212, v56, v1
	v_fma_f32 v0, v111, v143, v0
	v_fma_f32 v1, v213, v57, v1
	v_fma_f32 v0, v112, v144, v0
	v_fma_f32 v1, v214, v58, v1
	v_fma_f32 v0, v113, v145, v0
	v_fma_f32 v1, v215, v59, v1
	v_fma_f32 v0, v114, v146, v0
	v_fma_f32 v1, v216, v60, v1
	v_fma_f32 v0, v115, v147, v0
	v_fma_f32 v1, v217, v61, v1
	v_fma_f32 v0, v116, v148, v0
	v_fma_f32 v1, v218, v62, v1
	v_fma_f32 v0, v117, v149, v0
	v_fma_f32 v1, v219, v63, v1
	v_fma_f32 v0, v118, v150, v0
	v_fma_f32 v1, v220, v64, v1
	v_fma_f32 v0, v119, v151, v0
	v_fma_f32 v1, v221, v65, v1
	v_fma_f32 v0, v120, v152, v0
	v_fma_f32 v1, v222, v66, v1
	v_fma_f32 v0, v121, v153, v0
	v_fma_f32 v1, v223, v67, v1
	v_fma_f32 v0, v122, v154, v0
	v_fma_f32 v1, v224, v68, v1
	v_fma_f32 v0, v123, v155, v0
	v_fma_f32 v1, v225, v69, v1
	v_fma_f32 v0, v124, v156, v0
	v_fma_f32 v1, v226, v70, v1
	v_fma_f32 v0, v125, v157, v0
	v_fma_f32 v1, v227, v71, v1
	v_fma_f32 v0, v126, v158, v0
	v_fma_f32 v1, v228, v72, v1
	v_fma_f32 v0, v127, v159, v0
	v_fma_f32 v1, v229, v73, v1
	v_fma_f32 v0, v128, v160, v0
	v_fma_f32 v1, v230, v74, v1
	v_fma_f32 v0, v129, v161, v0
	v_fma_f32 v1, v231, v75, v1
	v_fma_f32 v0, v130, v162, v0
	v_fma_f32 v1, v232, v76, v1
	v_fma_f32 v0, v131, v163, v0
	v_fma_f32 v1, v233, v77, v1
	v_fma_f32 v0, v132, v164, v0
	v_fma_f32 v1, v234, v78, v1
	v_fma_f32 v0, v133, v165, v0
	v_fma_f32 v1, v235, v79, v1
	s_mov_b32 s11, s94
	s_add_i32 s10, s10, 8
	s_cmp_ge_i32 s11, s10
	s_cbranch_scc1 .LBB0_601
	v_cvt_f32_u32_e32 v2, s26
	v_mul_f32_e32 v0, 0x3fb8aa3b, v0
	v_mul_f32_e32 v1, 0x3fb8aa3b, v1
	v_exp_f32_e32 v0, v0
	v_mul_f32_e32 v2, 0xbe99999a, v2
	v_mul_f32_e32 v2, 0x3fb8aa3b, v2
	v_exp_f32_e32 v1, v1
	v_exp_f32_e32 v2, v2
	s_lshl_b32 s54, s26, 6
	s_lshl_b64 s[6:7], s[54:55], 2
	v_sub_f32_e32 v0, v0, v1
	v_mov_b32_e32 v1, 0x3f4ccccd
	v_fmamk_f32 v1, v2, 0xbf19999a, v1
	v_add_f32_e32 v204, v1, v0
	v_sub_f32_e32 v205, 1.0, v1
	s_branch .LBB0_575
